# QKV-ATT seam narrowed from the 32 workgroups of a batch to the 8 that produce this workgroup's (batch, head-group) Q/K/V tiles
# speedup vs baseline: 1.0063x; 1.0063x over previous
.LBB0_1611:
	s_and_b64 vcc, exec, s[0:1]
	s_cbranch_vccz .LBB0_1629
	s_waitcnt vmcnt(0)
	s_waitcnt vmcnt(0)
	s_barrier
	s_mov_b64 s[0:1], exec
	v_readlane_b32 s2, v249, 10
	v_readlane_b32 s3, v249, 11
	s_and_b64 s[2:3], s[0:1], s[2:3]
	s_mov_b64 exec, s[2:3]
	s_cbranch_execz .LBB0_1628
	s_and_b32 s2, s81, 7
	s_lshr_b32 s4, s81, 6
	s_lshl_b32 s4, s4, 3
	s_or_b32 s2, s2, s4
	s_lshl_b32 s2, s2, 8
	s_mov_b64 s[4:5], exec
	s_add_u32 s2, s82, s2
	s_addc_u32 s3, s83, 0
	v_readlane_b32 s98, v250, 1
	s_cmp_lg_u32 s98, 0
	s_cbranch_scc1 .Lskip_wbl2_3
	buffer_wbl2 sc1
.Lskip_wbl2_3:
	s_waitcnt vmcnt(0)
	v_mbcnt_lo_u32_b32 v1, s4, 0
	s_add_u32 s2, s2, 0x31000
	v_mbcnt_hi_u32_b32 v2, s5, v1
	s_addc_u32 s3, s3, 0
	v_cmp_eq_u32_e32 vcc, 0, v2
	s_and_saveexec_b64 s[6:7], vcc
	s_cbranch_execz .LBB0_1615
	s_bcnt1_i32_b64 s4, s[4:5]
	v_mov_b32_e32 v1, 0
	v_mov_b32_e32 v3, s4
	global_atomic_add v3, v1, v3, s[2:3] sc0
.LBB0_1615:
	s_or_b64 exec, exec, s[6:7]
	v_mov_b32_e32 v1, 0
	global_load_dword v4, v1, s[2:3] sc1
	s_waitcnt vmcnt(1)
	v_readfirstlane_b32 s4, v3
	s_nop 1
	v_add_u32_e32 v2, s4, v2
	v_and_b32_e32 v2, -8, v2
	v_add_u32_e32 v2, 8, v2
	s_waitcnt vmcnt(0)
	v_cmp_lt_u32_e32 vcc, v4, v2
	s_and_saveexec_b64 s[4:5], vcc
	s_cbranch_execz .LBB0_1627
	s_add_u32 s6, s82, 0x4200
	s_addc_u32 s7, s83, 0
	s_mov_b32 s18, 1
	s_mov_b64 s[8:9], 0
	s_branch .LBB0_1618
